# diff-attention tile loops: 2-deep register prefetch (K/V loads issued two tiles ahead into alternating register sets; loop top split by tile parity)
# baseline (speedup 1.0000x reference)
; #define GLOAD(K0, K1, V0, V1, kvt) do { const size_t ko_ = (size_t)(kvt) * 64 * QKVW; const int vo_ = (kvt) * 64; \
;         K0 = *(const u32x4*)(kg0 + ko_); K1 = *(const u32x4*)(kg1 + ko_); V0 = *(const u32x4*)(vg0 + vo_); V1 = *(const u32x4*)(vg1 + vo_); } while (0)
; #define STEP_LEAD(kvt, kslot, vso) do { f32x16 p0, p1; bool act, lval; \
;             QK_TILE(kvt, kslot); \
;             if (act) { SOFTMAX_HALF(p0, pa0, pb0); PV_HALF(vso, 0, pa0, pb0); SOFTMAX_HALF(p1, pa1, pb1); PV_HALF(vso, 2, pa1, pb1); } \
;         } while (0)
; #define STEP_TRAIL(kvt, kslot, vso) do { f32x16 p0, p1; bool act, lval; \
;             if (actp) { PV_HALF(vsp, 0, pa0, pb0); PV_HALF(vsp, 2, pa1, pb1); } \
;             QK_TILE(kvt, kslot); \
;             if (act) { SOFTMAX_FULL(p0, p1, pa0, pb0, pa1, pb1); } \
;             actp = act; vsp = (vso); \
;         } while (0)
; template <int MODE> ...
;     ...
;     bf16x8 qf[NDK];
;     { const bf16_t* qp = QKV + (tokbase + qpos) * QKVW + qcol + hi * 8;
; #pragma unroll
;       for (int dk = 0; dk < NDK; ++dk) qf[dk] = *(const bf16x8*)(qp + dk * 16); }
;     float m = NEG, l = 0.f;
;     f32x16 o[4];
; #pragma unroll
;     for (int i = 0; i < 4; ++i)
; #pragma unroll
;         for (int r = 0; r < 16; ++r) o[i][r] = 0.f;
;     u32x4 kr0, kr1, vr0, vr1;
;     const int idA = tid, idB = tid + 512;
;     const bf16_t* kg0 = QKV + (tokbase + (idA >> 4)) * QKVW + kcol + (idA & 15) * 8;
;     const bf16_t* kg1 = QKV + (tokbase + (idB >> 4)) * QKVW + kcol + (idB & 15) * 8;
;     const bf16_t* vg0 = VTb + (size_t)(idA >> 3) * SEQ + (idA & 7) * 8;
;     const bf16_t* vg1 = VTb + (size_t)(idB >> 3) * SEQ + (idB & 7) * 8;
;     const int kl0 = (idA >> 4) * KP + (idA & 15) * 16, kl1 = (idB >> 4) * KP + (idB & 15) * 16;
;     const int vl0 = VRING + (idA >> 3) * VP + ((idA & 7) >> 1) * 32 + (idA & 1) * 8, vl1 = VRING + (idB >> 3) * VP + ((idB & 7) >> 1) * 32 + (idB & 1) * 8;
;     ...
;     GLOAD(kr0, kr1, vr0, vr1, TILE_AT(0));
;     if (trailing) {
;         TILE_LOOP(STEP_TRAIL);
;         if (actp) { PV_HALF(vsp, 0, pa0, pb0); PV_HALF(vsp, 2, pa1, pb1); }
;     } else {
;         TILE_LOOP(STEP_LEAD);
.LBB0_264:
	v_mov_b32_e32 v14, v202
	s_lshl_b32 s28, s29, 7
	v_readfirstlane_b32 s4, v14
	s_ashr_i32 s79, s4, 2
	s_andn2_b32 s79, s79, 31
	v_and_b32_e32 v167, 31, v14
	s_add_i32 s80, s79, s28
	s_ashr_i32 s54, s4, 6
	s_waitcnt vmcnt(16)
	v_or_b32_e32 v146, s80, v167
	s_and_b32 s78, s54, 1
	v_ashrrev_i32_e32 v147, 31, v146
	s_lshl_b32 s55, s78, 6
	v_lshl_add_u64 v[144:145], s[14:15], 0, v[146:147]
	v_mov_b64_e32 v[0:1], s[68:69]
	s_or_b32 s24, s55, s1
	v_mad_u64_u32 v[0:1], s[4:5], v144, s35, v[0:1]
	v_bfe_u32 v64, v14, 5, 1
	v_mad_i32_i24 v1, v145, s35, v1
	s_lshl_b32 s24, s24, 1
	v_lshl_add_u64 v[0:1], v[0:1], 0, s[24:25]
	v_lshlrev_b32_e32 v160, 4, v64
	v_lshl_add_u64 v[0:1], v[0:1], 0, v[160:161]
	global_load_dwordx4 v[96:99], v[0:1], off
	global_load_dwordx4 v[100:103], v[0:1], off offset:32
	global_load_dwordx4 v[104:107], v[0:1], off offset:64
	global_load_dwordx4 v[108:111], v[0:1], off offset:96
	v_ashrrev_i32_e32 v0, 4, v14
	v_ashrrev_i32_e32 v1, 31, v0
	v_lshl_add_u64 v[2:3], s[14:15], 0, v[0:1]
	v_mov_b64_e32 v[4:5], s[44:45]
	v_mad_u64_u32 v[6:7], s[4:5], v2, s35, v[4:5]
	v_lshlrev_b32_e32 v1, 4, v14
	v_add_u32_e32 v12, 0x200, v14
	v_mad_i32_i24 v7, v3, s35, v7
	v_and_b32_e32 v2, 0xf0, v1
	v_mov_b32_e32 v3, v161
	v_lshl_add_u64 v[148:149], v[6:7], 0, v[2:3]
	v_ashrrev_i32_e32 v6, 4, v12
	v_ashrrev_i32_e32 v7, 31, v6
	v_lshl_add_u64 v[8:9], s[14:15], 0, v[6:7]
	v_mad_u64_u32 v[4:5], s[4:5], v8, s35, v[4:5]
	v_mad_i32_i24 v5, v9, s35, v5
	v_lshl_add_u64 v[150:151], v[4:5], 0, v[2:3]
	v_ashrrev_i32_e32 v4, 3, v14
	v_ashrrev_i32_e32 v5, 31, v4
	v_lshlrev_b64 v[8:9], 13, v[4:5]
	v_and_b32_e32 v3, 7, v14
	v_lshl_add_u64 v[8:9], s[42:43], 0, v[8:9]
	v_lshlrev_b32_e32 v10, 4, v3
	v_mov_b32_e32 v11, v161
	v_lshl_add_u64 v[152:153], v[8:9], 0, v[10:11]
	v_ashrrev_i32_e32 v8, 3, v12
	v_ashrrev_i32_e32 v9, 31, v8
	v_lshlrev_b64 v[12:13], 13, v[8:9]
	v_lshl_add_u64 v[12:13], s[42:43], 0, v[12:13]
	v_lshl_add_u64 v[154:155], v[12:13], 0, v[10:11]
	global_load_dwordx4 v[116:119], v[148:149], off offset:2048
	global_load_dwordx4 v[120:123], v[150:151], off offset:2048
	global_load_dwordx4 v[124:127], v[152:153], off
	global_load_dwordx4 v[112:115], v[154:155], off
	v_lshlrev_b32_e32 v3, 3, v64
	v_mad_u64_u32 v[156:157], s[4:5], v0, s49, v[2:3]
	v_mad_u64_u32 v[158:159], s[4:5], v6, s49, v[2:3]
	v_lshlrev_b32_e32 v2, 3, v14
	s_lshl_b32 s24, s29, 1
	v_and_b32_e32 v1, 0x60, v1
	v_and_b32_e32 v2, 8, v2
	s_add_i32 s81, s24, 2
	v_mul_lo_u32 v0, v4, s23
	v_mul_lo_u32 v4, v8, s23
	v_or_b32_e32 v5, v1, v2
	s_or_b32 s86, s24, 1
	v_or_b32_e32 v3, s55, v3
	s_cmp_gt_i32 s54, 3
	s_mov_b64 s[4:5], -1
	v_mul_u32_u24_e32 v159, 0x110, v167
	v_mul_u32_u24_e32 v157, 0x90, v167
	v_add3_u32 v169, v0, v2, v1
	v_add_u32_e32 v170, v5, v4
	v_lshlrev_b32_e32 v171, 1, v3
	v_lshlrev_b32_e32 v147, 2, v64
	s_cbranch_scc1 .LBB0_278
	v_mov_b32_e32 v14, v161
	v_mov_b32_e32 v15, v161
	v_mov_b32_e32 v0, v161
	v_mov_b32_e32 v1, v161
	v_mov_b32_e32 v2, v161
	v_mov_b32_e32 v3, v161
	v_mov_b32_e32 v4, v161
	v_mov_b32_e32 v5, v161
	v_mov_b32_e32 v6, v161
	v_mov_b32_e32 v7, v161
	v_mov_b32_e32 v8, v161
	v_mov_b32_e32 v9, v161
	v_mov_b32_e32 v10, v161
	v_mov_b32_e32 v11, v161
	v_mov_b32_e32 v12, v161
	v_mov_b32_e32 v13, v161
	v_mov_b64_e32 v[30:31], v[14:15]
	v_mov_b64_e32 v[46:47], v[14:15]
	v_mov_b64_e32 v[62:63], v[14:15]
	s_waitcnt vmcnt(3)
	v_mov_b64_e32 v[134:135], v[118:119]
	s_waitcnt vmcnt(2)
	v_mov_b64_e32 v[138:139], v[122:123]
	s_waitcnt vmcnt(1)
	v_mov_b64_e32 v[142:143], v[126:127]
	s_waitcnt vmcnt(0)
	v_mov_b64_e32 v[130:131], v[114:115]
	s_or_b32 s4, s80, 31
	s_mov_b32 s5, 1
	v_lshlrev_b32_e32 v166, 2, v64
	s_add_i32 s29, s28, 0x80
	s_mov_b32 s54, 0
	v_mov_b32_e32 v172, 0
	v_mov_b32_e32 v173, 0xf149f2ca
	v_mov_b64_e32 v[28:29], v[12:13]
	v_mov_b64_e32 v[26:27], v[10:11]
	v_mov_b64_e32 v[24:25], v[8:9]
	v_mov_b64_e32 v[22:23], v[6:7]
	v_mov_b64_e32 v[20:21], v[4:5]
	v_mov_b64_e32 v[18:19], v[2:3]
	v_mov_b64_e32 v[16:17], v[0:1]
	v_mov_b64_e32 v[44:45], v[12:13]
	v_mov_b64_e32 v[42:43], v[10:11]
	v_mov_b64_e32 v[40:41], v[8:9]
	v_mov_b64_e32 v[38:39], v[6:7]
	v_mov_b64_e32 v[36:37], v[4:5]
	v_mov_b64_e32 v[34:35], v[2:3]
	v_mov_b64_e32 v[32:33], v[0:1]
	v_mov_b64_e32 v[60:61], v[12:13]
	v_mov_b64_e32 v[58:59], v[10:11]
	v_mov_b64_e32 v[56:57], v[8:9]
	v_mov_b64_e32 v[54:55], v[6:7]
	v_mov_b64_e32 v[52:53], v[4:5]
	v_mov_b64_e32 v[50:51], v[2:3]
	v_mov_b64_e32 v[48:49], v[0:1]
	v_mov_b64_e32 v[132:133], v[116:117]
	v_mov_b64_e32 v[136:137], v[120:121]
	v_mov_b64_e32 v[140:141], v[124:125]
	v_mov_b64_e32 v[128:129], v[112:113]
	s_mov_b32 s55, 0
	s_mov_b32 s87, 0
	v_mad_u64_u32 v[64:65], s[90:91], 1, v215, v[148:149]
	v_mad_u64_u32 v[66:67], s[90:91], 1, v215, v[150:151]
	global_load_dwordx4 v[226:229], v[64:65], off offset:2048
	global_load_dwordx4 v[230:233], v[66:67], off offset:2048
	global_load_dwordx4 v[234:237], v[152:153], off offset:128
	global_load_dwordx4 v[222:225], v[154:155], off offset:128
	s_branch .LBB0_269

.LBB0_269:
	s_add_i32 s92, s5, 1
	s_min_u32 s92, s92, s86
	s_lshl_b32 s24, s92, 6
	s_bitcmp1_b32 s5, 0
	s_cbranch_scc0 .Ldb_m0l_odd
	s_add_i32 s89, s55, 0
	v_add_u32_e32 v64, s89, v156
	s_add_i32 s88, s87, 0
	s_waitcnt vmcnt(7)
	ds_write_b128 v64, v[132:135]
	v_add_u32_e32 v64, s89, v158
	s_waitcnt vmcnt(6)
	ds_write_b128 v64, v[136:139]
	v_add_u32_e32 v64, s88, v169
	v_add_u32_e32 v64, 0x8800, v64
	s_waitcnt vmcnt(5)
	ds_write2_b64 v64, v[140:141], v[142:143] offset1:2
	v_add_u32_e32 v64, s88, v170
	v_add_u32_e32 v64, 0x8800, v64
	s_waitcnt vmcnt(4)
	ds_write2_b64 v64, v[128:129], v[130:131] offset1:2
	v_mad_u64_u32 v[64:65], s[90:91], s92, v215, v[148:149]
	v_mad_u64_u32 v[66:67], s[90:91], s92, v215, v[150:151]
	s_waitcnt lgkmcnt(0)
	s_barrier
	s_lshl_b64 s[90:91], s[24:25], 1
	global_load_dwordx4 v[132:135], v[64:65], off offset:2048
	global_load_dwordx4 v[136:139], v[66:67], off offset:2048
	v_lshl_add_u64 v[64:65], v[152:153], 0, s[90:91]
	v_lshl_add_u64 v[66:67], v[154:155], 0, s[90:91]
	global_load_dwordx4 v[140:143], v[64:65], off
	global_load_dwordx4 v[128:131], v[66:67], off
	s_branch .Ldb_m0l_join
.Ldb_m0l_odd:
	s_add_i32 s89, s55, 0
	v_add_u32_e32 v64, s89, v156
	s_add_i32 s88, s87, 0
	s_waitcnt vmcnt(7)
	ds_write_b128 v64, v[226:229]
	v_add_u32_e32 v64, s89, v158
	s_waitcnt vmcnt(6)
	ds_write_b128 v64, v[230:233]
	v_add_u32_e32 v64, s88, v169
	v_add_u32_e32 v64, 0x8800, v64
	s_waitcnt vmcnt(5)
	ds_write2_b64 v64, v[234:235], v[236:237] offset1:2
	v_add_u32_e32 v64, s88, v170
	v_add_u32_e32 v64, 0x8800, v64
	s_waitcnt vmcnt(4)
	ds_write2_b64 v64, v[222:223], v[224:225] offset1:2
	v_mad_u64_u32 v[64:65], s[90:91], s92, v215, v[148:149]
	v_mad_u64_u32 v[66:67], s[90:91], s92, v215, v[150:151]
	s_waitcnt lgkmcnt(0)
	s_barrier
	s_lshl_b64 s[90:91], s[24:25], 1
	global_load_dwordx4 v[226:229], v[64:65], off offset:2048
	global_load_dwordx4 v[230:233], v[66:67], off offset:2048
	v_lshl_add_u64 v[64:65], v[152:153], 0, s[90:91]
	v_lshl_add_u64 v[66:67], v[154:155], 0, s[90:91]
	global_load_dwordx4 v[234:237], v[64:65], off
	global_load_dwordx4 v[222:225], v[66:67], off
.Ldb_m0l_join:
	s_cmp_gt_i32 s54, s4
	s_cbranch_scc1 .LBB0_268
	v_add3_u32 v76, s89, v159, v171
	ds_read_b128 v[64:67], v76
	ds_read_b128 v[68:71], v76 offset:32
	ds_read_b128 v[72:75], v76 offset:64
	ds_read_b128 v[174:177], v76 offset:96
	s_add_i32 s24, s54, 63
	s_cmp_le_i32 s24, s80
	s_waitcnt lgkmcnt(3)
	v_mfma_f32_32x32x16_bf16 v[80:95], v[64:67], v[96:99], 0
	s_waitcnt lgkmcnt(2)
	v_mfma_f32_32x32x16_bf16 v[80:95], v[68:71], v[100:103], v[80:95]
	ds_read_b128 v[64:67], v76 offset:8704
	ds_read_b128 v[178:181], v76 offset:8736
	ds_read_b128 v[186:189], v76 offset:8768
	ds_read_b128 v[190:193], v76 offset:8800
	s_waitcnt lgkmcnt(5)
	v_mfma_f32_32x32x16_bf16 v[80:95], v[72:75], v[104:107], v[80:95]
	s_waitcnt lgkmcnt(3)
	v_mfma_f32_32x32x16_bf16 v[64:79], v[64:67], v[96:99], 0
	s_waitcnt lgkmcnt(2)
	v_mfma_f32_32x32x16_bf16 v[64:79], v[178:181], v[100:103], v[64:79]
	s_waitcnt lgkmcnt(1)
	v_mfma_f32_32x32x16_bf16 v[64:79], v[186:189], v[104:107], v[64:79]
	s_waitcnt lgkmcnt(0)
	v_mfma_f32_32x32x16_bf16 v[64:79], v[190:193], v[108:111], v[64:79]
	v_mfma_f32_32x32x16_bf16 v[80:95], v[174:177], v[108:111], v[80:95]
	s_cbranch_scc1 .LBB0_272
	v_add_u32_e32 v168, s54, v166
	v_add_u32_e32 v174, 32, v168
	v_cmp_le_i32_e32 vcc, v174, v146
	v_add_u32_e32 v174, 33, v168
	s_nop 5
	v_cndmask_b32_e32 v64, v213, v64, vcc
	v_cmp_lt_i32_e32 vcc, v168, v146
	s_nop 1
	v_cndmask_b32_e32 v81, v213, v81, vcc
	v_cmp_le_i32_e32 vcc, v168, v146
	s_nop 1
	v_cndmask_b32_e32 v80, v213, v80, vcc
	v_cmp_le_i32_e32 vcc, v174, v146
	v_add_u32_e32 v174, 2, v168
	s_nop 0
	v_cndmask_b32_e32 v65, v213, v65, vcc
	v_cmp_le_i32_e32 vcc, v174, v146
	v_add_u32_e32 v174, 34, v168
	s_nop 0
	v_cndmask_b32_e32 v82, v213, v82, vcc
	v_cmp_le_i32_e32 vcc, v174, v146
	v_add_u32_e32 v174, 3, v168
	s_nop 0
	v_cndmask_b32_e32 v66, v213, v66, vcc
	v_cmp_le_i32_e32 vcc, v174, v146
	v_add_u32_e32 v174, 35, v168
	s_nop 0
	v_cndmask_b32_e32 v83, v213, v83, vcc
	v_cmp_le_i32_e32 vcc, v174, v146
	v_add_u32_e32 v174, 8, v168
	s_nop 0
	v_cndmask_b32_e32 v67, v213, v67, vcc
	v_cmp_le_i32_e32 vcc, v174, v146
	v_add_u32_e32 v174, 40, v168
	s_nop 0
	v_cndmask_b32_e32 v84, v213, v84, vcc
	v_cmp_le_i32_e32 vcc, v174, v146
	v_add_u32_e32 v174, 9, v168
	s_nop 0
	v_cndmask_b32_e32 v68, v213, v68, vcc
	v_cmp_le_i32_e32 vcc, v174, v146
	v_add_u32_e32 v174, 41, v168
	s_nop 0
	v_cndmask_b32_e32 v85, v213, v85, vcc
	v_cmp_le_i32_e32 vcc, v174, v146
	v_add_u32_e32 v174, 10, v168
	s_nop 0
	v_cndmask_b32_e32 v69, v213, v69, vcc
	v_cmp_le_i32_e32 vcc, v174, v146
	v_add_u32_e32 v174, 42, v168
	s_nop 0
	v_cndmask_b32_e32 v86, v213, v86, vcc
	v_cmp_le_i32_e32 vcc, v174, v146
	v_add_u32_e32 v174, 11, v168
	s_nop 0
	v_cndmask_b32_e32 v70, v213, v70, vcc
	v_cmp_le_i32_e32 vcc, v174, v146
	v_add_u32_e32 v174, 43, v168
	s_nop 0
	v_cndmask_b32_e32 v87, v213, v87, vcc
	v_cmp_le_i32_e32 vcc, v174, v146
	v_add_u32_e32 v174, 16, v168
	s_nop 0
	v_cndmask_b32_e32 v71, v213, v71, vcc
	v_cmp_le_i32_e32 vcc, v174, v146
	v_add_u32_e32 v174, 48, v168
	s_nop 0
	v_cndmask_b32_e32 v88, v213, v88, vcc
	v_cmp_le_i32_e32 vcc, v174, v146
	v_add_u32_e32 v174, 17, v168
	s_nop 0
	v_cndmask_b32_e32 v72, v213, v72, vcc
	v_cmp_le_i32_e32 vcc, v174, v146
	v_add_u32_e32 v174, 49, v168
	s_nop 0
	v_cndmask_b32_e32 v89, v213, v89, vcc
	v_cmp_le_i32_e32 vcc, v174, v146
	v_add_u32_e32 v174, 18, v168
	s_nop 0
	v_cndmask_b32_e32 v73, v213, v73, vcc
	v_cmp_le_i32_e32 vcc, v174, v146
	v_add_u32_e32 v174, 50, v168
	s_nop 0
	v_cndmask_b32_e32 v90, v213, v90, vcc
	v_cmp_le_i32_e32 vcc, v174, v146
	v_add_u32_e32 v174, 19, v168
	s_nop 0
	v_cndmask_b32_e32 v74, v213, v74, vcc
	v_cmp_le_i32_e32 vcc, v174, v146
	v_add_u32_e32 v174, 51, v168
	s_nop 0
	v_cndmask_b32_e32 v91, v213, v91, vcc
	v_cmp_le_i32_e32 vcc, v174, v146
	v_add_u32_e32 v174, 24, v168
	s_nop 0
	v_cndmask_b32_e32 v75, v213, v75, vcc
	v_cmp_le_i32_e32 vcc, v174, v146
	v_add_u32_e32 v174, 56, v168
	s_nop 0
	v_cndmask_b32_e32 v92, v213, v92, vcc
	v_cmp_le_i32_e32 vcc, v174, v146
	v_add_u32_e32 v174, 25, v168
	s_nop 0
	v_cndmask_b32_e32 v76, v213, v76, vcc
	v_cmp_le_i32_e32 vcc, v174, v146
	v_add_u32_e32 v174, 57, v168
	s_nop 0
	v_cndmask_b32_e32 v93, v213, v93, vcc
	v_cmp_le_i32_e32 vcc, v174, v146
	v_add_u32_e32 v174, 26, v168
	s_nop 0
	v_cndmask_b32_e32 v77, v213, v77, vcc
	v_cmp_le_i32_e32 vcc, v174, v146
	v_add_u32_e32 v174, 58, v168
	s_nop 0
	v_cndmask_b32_e32 v94, v213, v94, vcc
	v_cmp_le_i32_e32 vcc, v174, v146
	v_add_u32_e32 v174, 27, v168
	v_add_u32_e32 v168, 59, v168
	v_cndmask_b32_e32 v78, v213, v78, vcc
	v_cmp_le_i32_e32 vcc, v174, v146
	s_nop 1
	v_cndmask_b32_e32 v95, v213, v95, vcc
	v_cmp_le_i32_e32 vcc, v168, v146
	s_nop 1
	v_cndmask_b32_e32 v79, v213, v79, vcc

; #define GLOAD(K0, K1, V0, V1, kvt) do { const size_t ko_ = (size_t)(kvt) * 64 * QKVW; const int vo_ = (kvt) * 64; \
;         K0 = *(const u32x4*)(kg0 + ko_); K1 = *(const u32x4*)(kg1 + ko_); V0 = *(const u32x4*)(vg0 + vo_); V1 = *(const u32x4*)(vg1 + vo_); } while (0)
; #define STEP_TRAIL(kvt, kslot, vso) do { f32x16 p0, p1; bool act, lval; \
;             if (actp) { PV_HALF(vsp, 0, pa0, pb0); PV_HALF(vsp, 2, pa1, pb1); } \
;             QK_TILE(kvt, kslot); \
;             if (act) { SOFTMAX_FULL(p0, p1, pa0, pb0, pa1, pb1); } \
;             actp = act; vsp = (vso); \
;         } while (0)
; template <int MODE> ...
;     ...
;     const bool trailing = wid >= 4;
;     bf16x8 pa0, pb0, pa1, pb1; bool actp = false; int vsp = 0;
;     ...
;     GLOAD(kr0, kr1, vr0, vr1, TILE_AT(0));
;     if (trailing) {
;         TILE_LOOP(STEP_TRAIL);
.LBB0_278:
	s_and_b64 vcc, exec, s[4:5]
	s_cbranch_vccz .LBB0_294
	v_mov_b32_e32 v14, v161
	v_mov_b32_e32 v15, v161
	v_mov_b32_e32 v0, v161
	v_mov_b32_e32 v1, v161
	v_mov_b32_e32 v2, v161
	v_mov_b32_e32 v3, v161
	v_mov_b32_e32 v4, v161
	v_mov_b32_e32 v5, v161
	v_mov_b32_e32 v6, v161
	v_mov_b32_e32 v7, v161
	v_mov_b32_e32 v8, v161
	v_mov_b32_e32 v9, v161
	v_mov_b32_e32 v10, v161
	v_mov_b32_e32 v11, v161
	v_mov_b32_e32 v12, v161
	v_mov_b32_e32 v13, v161
	v_mov_b64_e32 v[30:31], v[14:15]
	v_mov_b64_e32 v[46:47], v[14:15]
	v_mov_b64_e32 v[62:63], v[14:15]
	s_or_b32 s4, s80, 31
	s_mov_b32 s5, 1
	s_waitcnt vmcnt(0)
	v_add3_u32 v129, 0, v157, v160
	s_addk_i32 s28, 0x80
	s_mov_b32 s29, 0
	s_mov_b64 s[54:55], 0
	v_mov_b32_e32 v172, 0
	v_mov_b32_e32 v130, 0xf149f2ca
	v_mov_b64_e32 v[28:29], v[12:13]
	v_mov_b64_e32 v[26:27], v[10:11]
	v_mov_b64_e32 v[24:25], v[8:9]
	v_mov_b64_e32 v[22:23], v[6:7]
	v_mov_b64_e32 v[20:21], v[4:5]
	v_mov_b64_e32 v[18:19], v[2:3]
	v_mov_b64_e32 v[16:17], v[0:1]
	v_mov_b64_e32 v[44:45], v[12:13]
	v_mov_b64_e32 v[42:43], v[10:11]
	v_mov_b64_e32 v[40:41], v[8:9]
	v_mov_b64_e32 v[38:39], v[6:7]
	v_mov_b64_e32 v[36:37], v[4:5]
	v_mov_b64_e32 v[34:35], v[2:3]
	v_mov_b64_e32 v[32:33], v[0:1]
	v_mov_b64_e32 v[60:61], v[12:13]
	v_mov_b64_e32 v[58:59], v[10:11]
	v_mov_b64_e32 v[56:57], v[8:9]
	v_mov_b64_e32 v[54:55], v[6:7]
	v_mov_b64_e32 v[52:53], v[4:5]
	v_mov_b64_e32 v[50:51], v[2:3]
	v_mov_b64_e32 v[48:49], v[0:1]
	s_mov_b32 s91, 0
	s_mov_b32 s87, 0
	s_mov_b32 s88, 0
	v_mad_u64_u32 v[72:73], s[92:93], 1, v215, v[148:149]
	v_mad_u64_u32 v[74:75], s[92:93], 1, v215, v[150:151]
	global_load_dwordx4 v[242:245], v[72:73], off offset:2048
	global_load_dwordx4 v[246:249], v[74:75], off offset:2048
	global_load_dwordx4 v[250:253], v[152:153], off offset:128
	global_load_dwordx4 v[238:241], v[154:155], off offset:128
.LBB0_280:
	s_add_i32 s94, s5, 1
	s_min_u32 s94, s94, s86
	s_lshl_b32 s24, s94, 6
	s_bitcmp1_b32 s5, 0
	s_cbranch_scc0 .Ldb_m0t_odd
	s_add_i32 s90, s88, 0
	v_add_u32_e32 v72, s90, v156
	s_add_i32 s89, s87, 0
	s_waitcnt vmcnt(7)
	ds_write_b128 v72, v[116:119]
	v_add_u32_e32 v72, s90, v158
	s_waitcnt vmcnt(6)
	ds_write_b128 v72, v[120:123]
	v_add_u32_e32 v72, s89, v169
	v_add_u32_e32 v72, 0x8800, v72
	s_waitcnt vmcnt(5)
	ds_write2_b64 v72, v[124:125], v[126:127] offset1:2
	v_add_u32_e32 v72, s89, v170
	v_add_u32_e32 v72, 0x8800, v72
	s_waitcnt vmcnt(4)
	ds_write2_b64 v72, v[112:113], v[114:115] offset1:2
	v_mad_u64_u32 v[72:73], s[92:93], s94, v215, v[148:149]
	v_mad_u64_u32 v[74:75], s[92:93], s94, v215, v[150:151]
	s_waitcnt lgkmcnt(0)
	s_barrier
	s_lshl_b64 s[92:93], s[24:25], 1
	global_load_dwordx4 v[116:119], v[72:73], off offset:2048
	global_load_dwordx4 v[120:123], v[74:75], off offset:2048
	v_lshl_add_u64 v[72:73], v[152:153], 0, s[92:93]
	v_lshl_add_u64 v[74:75], v[154:155], 0, s[92:93]
	global_load_dwordx4 v[124:127], v[72:73], off
	global_load_dwordx4 v[112:115], v[74:75], off
	s_branch .Ldb_m0t_join
.Ldb_m0t_odd:
	s_add_i32 s90, s88, 0
	v_add_u32_e32 v72, s90, v156
	s_add_i32 s89, s87, 0
	s_waitcnt vmcnt(7)
	ds_write_b128 v72, v[242:245]
	v_add_u32_e32 v72, s90, v158
	s_waitcnt vmcnt(6)
	ds_write_b128 v72, v[246:249]
	v_add_u32_e32 v72, s89, v169
	v_add_u32_e32 v72, 0x8800, v72
	s_waitcnt vmcnt(5)
	ds_write2_b64 v72, v[250:251], v[252:253] offset1:2
	v_add_u32_e32 v72, s89, v170
	v_add_u32_e32 v72, 0x8800, v72
	s_waitcnt vmcnt(4)
	ds_write2_b64 v72, v[238:239], v[240:241] offset1:2
	v_mad_u64_u32 v[72:73], s[92:93], s94, v215, v[148:149]
	v_mad_u64_u32 v[74:75], s[92:93], s94, v215, v[150:151]
	s_waitcnt lgkmcnt(0)
	s_barrier
	s_lshl_b64 s[92:93], s[24:25], 1
	global_load_dwordx4 v[242:245], v[72:73], off offset:2048
	global_load_dwordx4 v[246:249], v[74:75], off offset:2048
	v_lshl_add_u64 v[72:73], v[152:153], 0, s[92:93]
	v_lshl_add_u64 v[74:75], v[154:155], 0, s[92:93]
	global_load_dwordx4 v[250:253], v[72:73], off
	global_load_dwordx4 v[238:241], v[74:75], off
.Ldb_m0t_join:
	s_andn2_b64 vcc, exec, s[54:55]
	s_cbranch_vccnz .LBB0_282
	v_add_u32_e32 v128, s91, v129
	ds_read_b128 v[72:75], v128 offset:34816
	ds_read_b128 v[76:79], v128 offset:34848
	ds_read_b128 v[88:91], v128 offset:39424
	ds_read_b128 v[92:95], v128 offset:39456
	s_waitcnt lgkmcnt(3)
	v_mfma_f32_32x32x16_bf16 v[48:63], v[72:75], v[80:83], v[48:63]
	s_waitcnt lgkmcnt(1)
	v_mfma_f32_32x32x16_bf16 v[32:47], v[88:91], v[80:83], v[32:47]
	v_mfma_f32_32x32x16_bf16 v[48:63], v[76:79], v[84:87], v[48:63]
	s_waitcnt lgkmcnt(0)
	v_mfma_f32_32x32x16_bf16 v[32:47], v[92:95], v[84:87], v[32:47]
	ds_read_b128 v[72:75], v128 offset:44032
	ds_read_b128 v[76:79], v128 offset:44064
	ds_read_b128 v[88:91], v128 offset:48640
	ds_read_b128 v[92:95], v128 offset:48672
	s_waitcnt lgkmcnt(3)
	v_mfma_f32_32x32x16_bf16 v[16:31], v[72:75], v[80:83], v[16:31]
	s_waitcnt lgkmcnt(1)
	v_mfma_f32_32x32x16_bf16 v[0:15], v[88:91], v[80:83], v[0:15]
	v_mfma_f32_32x32x16_bf16 v[16:31], v[76:79], v[84:87], v[16:31]
	s_waitcnt lgkmcnt(0)
	v_mfma_f32_32x32x16_bf16 v[0:15], v[92:95], v[84:87], v[0:15]
	ds_read_b128 v[72:75], v128 offset:34880
	ds_read_b128 v[76:79], v128 offset:34912
	ds_read_b128 v[88:91], v128 offset:39488
	ds_read_b128 v[92:95], v128 offset:39520
	s_waitcnt lgkmcnt(3)
	v_mfma_f32_32x32x16_bf16 v[48:63], v[72:75], v[64:67], v[48:63]
	s_waitcnt lgkmcnt(1)
	v_mfma_f32_32x32x16_bf16 v[32:47], v[88:91], v[64:67], v[32:47]
	v_mfma_f32_32x32x16_bf16 v[48:63], v[76:79], v[68:71], v[48:63]
	s_waitcnt lgkmcnt(0)
	v_mfma_f32_32x32x16_bf16 v[32:47], v[92:95], v[68:71], v[32:47]
	ds_read_b128 v[72:75], v128 offset:44096
	ds_read_b128 v[76:79], v128 offset:44128
	ds_read_b128 v[88:91], v128 offset:48704
	ds_read_b128 v[92:95], v128 offset:48736
	s_waitcnt lgkmcnt(3)
	v_mfma_f32_32x32x16_bf16 v[16:31], v[72:75], v[64:67], v[16:31]
	s_waitcnt lgkmcnt(1)
	v_mfma_f32_32x32x16_bf16 v[0:15], v[88:91], v[64:67], v[0:15]
	v_mfma_f32_32x32x16_bf16 v[16:31], v[76:79], v[68:71], v[16:31]
	s_waitcnt lgkmcnt(0)
	v_mfma_f32_32x32x16_bf16 v[0:15], v[92:95], v[68:71], v[0:15]
